# EpiRes: nt hint on f32 residual loads and out stores
# baseline (speedup 1.0000x reference)
.Lres_join:
	v_subrev_u32_e32 v0, s6, v176
	v_mov_b32_e32 v177, 0
	v_lshlrev_b64 v[204:205], 13, v[0:1]
	v_lshl_add_u64 v[204:205], v[204:205], 0, v[180:181]
	v_lshl_add_u64 v[246:247], s[44:45], 0, v[204:205]
	v_lshl_add_u64 v[248:249], s[42:43], 0, v[204:205]
	v_lshlrev_b64 v[204:205], 12, v[176:177]
	v_lshl_add_u64 v[204:205], s[66:67], 0, v[204:205]
	v_lshl_add_u64 v[250:251], v[178:179], 1, v[204:205]
	v_lshl_add_u64 v[198:199], v[176:177], 2, s[58:59]
	v_lshlrev_b32_e32 v200, 2, v212
	v_lshlrev_b32_e32 v201, 2, v211
	s_and_b64 vcc, exec, s[0:1]
	s_cbranch_vccnz .Lres_noaout
	global_load_dwordx4 v[230:233], v[246:247], off nt
	global_load_dwordx4 v[234:237], v[246:247], off offset:16 nt
	global_load_dwordx4 v[238:241], v[246:247], off offset:128 nt
	global_load_dwordx4 v[242:245], v[246:247], off offset:144 nt
	s_mov_b64 s[42:43], 0x20000
	v_lshl_add_u64 v[180:181], v[246:247], 0, s[42:43]
	global_load_dwordx4 v[146:149], v[180:181], off nt
	global_load_dwordx4 v[150:153], v[180:181], off offset:16 nt
	global_load_dwordx4 v[176:179], v[180:181], off offset:128 nt
	global_load_dwordx4 v[202:205], v[180:181], off offset:144 nt
	s_waitcnt vmcnt(4)
	v_pk_fma_f32 v[126:127], v[126:127], v[142:143], v[230:231]
	v_pk_fma_f32 v[128:129], v[128:129], v[144:145], v[232:233]
	v_pk_fma_f32 v[122:123], v[122:123], v[138:139], v[234:235]
	v_pk_fma_f32 v[124:125], v[124:125], v[140:141], v[236:237]
	v_pk_fma_f32 v[118:119], v[118:119], v[134:135], v[238:239]
	v_pk_fma_f32 v[120:121], v[120:121], v[136:137], v[240:241]
	v_pk_fma_f32 v[114:115], v[114:115], v[130:131], v[242:243]
	v_pk_fma_f32 v[116:117], v[116:117], v[132:133], v[244:245]
	global_store_dwordx4 v[248:249], v[126:129], off nt
	global_store_dwordx4 v[248:249], v[122:125], off offset:16 nt
	global_store_dwordx4 v[248:249], v[118:121], off offset:128 nt
	global_store_dwordx4 v[248:249], v[114:117], off offset:144 nt
	v_mul_f32_e32 v242, v126, v126
	v_fmac_f32_e32 v242, v127, v127
	v_fmac_f32_e32 v242, v128, v128
	v_fmac_f32_e32 v242, v129, v129
	v_fmac_f32_e32 v242, v122, v122
	v_fmac_f32_e32 v242, v123, v123
	v_fmac_f32_e32 v242, v124, v124
	v_fmac_f32_e32 v242, v125, v125
	v_mul_f32_e32 v243, v118, v118
	v_fmac_f32_e32 v243, v119, v119
	v_fmac_f32_e32 v243, v120, v120
	v_fmac_f32_e32 v243, v121, v121
	v_fmac_f32_e32 v243, v114, v114
	v_fmac_f32_e32 v243, v115, v115
	v_fmac_f32_e32 v243, v116, v116
	v_fmac_f32_e32 v243, v117, v117
	v_add_f32_e32 v242, v242, v243
	ds_bpermute_b32 v244, v200, v242
	v_pk_mul_f32 v[126:127], v[188:189], v[126:127]
	v_pk_mul_f32 v[128:129], v[190:191], v[128:129]
	v_pk_mul_f32 v[122:123], v[184:185], v[122:123]
	v_pk_mul_f32 v[124:125], v[186:187], v[124:125]
	v_pk_mul_f32 v[118:119], v[182:183], v[118:119]
	v_pk_mul_f32 v[120:121], v[196:197], v[120:121]
	v_pk_mul_f32 v[114:115], v[192:193], v[114:115]
	v_pk_mul_f32 v[116:117], v[194:195], v[116:117]
	v_cvt_pk_bf16_f32 v234, v126, v127
	v_cvt_pk_bf16_f32 v235, v128, v129
	v_cvt_pk_bf16_f32 v236, v122, v123
	v_cvt_pk_bf16_f32 v237, v124, v125
	v_cvt_pk_bf16_f32 v238, v118, v119
	v_cvt_pk_bf16_f32 v239, v120, v121
	v_cvt_pk_bf16_f32 v240, v114, v115
	v_cvt_pk_bf16_f32 v241, v116, v117
	global_store_dwordx4 v[250:251], v[234:237], off
	global_store_dwordx4 v[250:251], v[238:241], off offset:64
	s_waitcnt lgkmcnt(0)
	v_add_f32_e32 v242, v242, v244
	ds_bpermute_b32 v244, v201, v242
	s_waitcnt lgkmcnt(0)
	v_add_f32_e32 v242, v242, v244
	s_and_saveexec_b64 s[42:43], s[38:39]
	global_atomic_add_f32 v[198:199], v242, off
	s_mov_b64 exec, s[42:43]
	s_mov_b64 s[42:43], 0x40000
	v_lshl_add_u64 v[180:181], v[246:247], 0, s[42:43]
	global_load_dwordx4 v[230:233], v[180:181], off nt
	global_load_dwordx4 v[234:237], v[180:181], off offset:16 nt
	global_load_dwordx4 v[238:241], v[180:181], off offset:128 nt
	global_load_dwordx4 v[242:245], v[180:181], off offset:144 nt
	s_mov_b64 s[42:43], 0x60000
	v_lshl_add_u64 v[180:181], v[246:247], 0, s[42:43]
	global_load_dwordx4 v[126:129], v[180:181], off nt
	global_load_dwordx4 v[122:125], v[180:181], off offset:16 nt
	global_load_dwordx4 v[118:121], v[180:181], off offset:128 nt
	global_load_dwordx4 v[114:117], v[180:181], off offset:144 nt
	s_waitcnt vmcnt(15)
	v_pk_fma_f32 v[110:111], v[110:111], v[142:143], v[146:147]
	v_pk_fma_f32 v[112:113], v[112:113], v[144:145], v[148:149]
	v_pk_fma_f32 v[106:107], v[106:107], v[138:139], v[150:151]
	v_pk_fma_f32 v[108:109], v[108:109], v[140:141], v[152:153]
	v_pk_fma_f32 v[102:103], v[102:103], v[134:135], v[176:177]
	v_pk_fma_f32 v[104:105], v[104:105], v[136:137], v[178:179]
	v_pk_fma_f32 v[98:99], v[98:99], v[130:131], v[202:203]
	v_pk_fma_f32 v[100:101], v[100:101], v[132:133], v[204:205]
	s_mov_b64 s[42:43], 0x20000
	v_lshl_add_u64 v[146:147], v[248:249], 0, s[42:43]
	global_store_dwordx4 v[146:147], v[110:113], off nt
	global_store_dwordx4 v[146:147], v[106:109], off offset:16 nt
	global_store_dwordx4 v[146:147], v[102:105], off offset:128 nt
	global_store_dwordx4 v[146:147], v[98:101], off offset:144 nt
	v_mul_f32_e32 v202, v110, v110
	v_fmac_f32_e32 v202, v111, v111
	v_fmac_f32_e32 v202, v112, v112
	v_fmac_f32_e32 v202, v113, v113
	v_fmac_f32_e32 v202, v106, v106
	v_fmac_f32_e32 v202, v107, v107
	v_fmac_f32_e32 v202, v108, v108
	v_fmac_f32_e32 v202, v109, v109
	v_mul_f32_e32 v203, v102, v102
	v_fmac_f32_e32 v203, v103, v103
	v_fmac_f32_e32 v203, v104, v104
	v_fmac_f32_e32 v203, v105, v105
	v_fmac_f32_e32 v203, v98, v98
	v_fmac_f32_e32 v203, v99, v99
	v_fmac_f32_e32 v203, v100, v100
	v_fmac_f32_e32 v203, v101, v101
	v_add_f32_e32 v202, v202, v203
	ds_bpermute_b32 v204, v200, v202
	v_pk_mul_f32 v[110:111], v[188:189], v[110:111]
	v_pk_mul_f32 v[112:113], v[190:191], v[112:113]
	v_pk_mul_f32 v[106:107], v[184:185], v[106:107]
	v_pk_mul_f32 v[108:109], v[186:187], v[108:109]
	v_pk_mul_f32 v[102:103], v[182:183], v[102:103]
	v_pk_mul_f32 v[104:105], v[196:197], v[104:105]
	v_pk_mul_f32 v[98:99], v[192:193], v[98:99]
	v_pk_mul_f32 v[100:101], v[194:195], v[100:101]
	v_cvt_pk_bf16_f32 v150, v110, v111
	v_cvt_pk_bf16_f32 v151, v112, v113
	v_cvt_pk_bf16_f32 v152, v106, v107
	v_cvt_pk_bf16_f32 v153, v108, v109
	v_cvt_pk_bf16_f32 v176, v102, v103
	v_cvt_pk_bf16_f32 v177, v104, v105
	v_cvt_pk_bf16_f32 v178, v98, v99
	v_cvt_pk_bf16_f32 v179, v100, v101
	s_mov_b64 s[42:43], 0x10000
	v_lshl_add_u64 v[148:149], v[250:251], 0, s[42:43]
	global_store_dwordx4 v[148:149], v[150:153], off
	global_store_dwordx4 v[148:149], v[176:179], off offset:64
	s_waitcnt lgkmcnt(0)
	v_add_f32_e32 v202, v202, v204
	ds_bpermute_b32 v204, v201, v202
	s_waitcnt lgkmcnt(0)
	v_add_f32_e32 v202, v202, v204
	s_and_saveexec_b64 s[42:43], s[38:39]
	global_atomic_add_f32 v[198:199], v202, off offset:64
	s_mov_b64 exec, s[42:43]
	s_mov_b64 s[42:43], 0x100000
	v_lshl_add_u64 v[180:181], v[246:247], 0, s[42:43]
	global_load_dwordx4 v[146:149], v[180:181], off nt
	global_load_dwordx4 v[150:153], v[180:181], off offset:16 nt
	global_load_dwordx4 v[176:179], v[180:181], off offset:128 nt
	global_load_dwordx4 v[202:205], v[180:181], off offset:144 nt
	s_mov_b64 s[42:43], 0x120000
	v_lshl_add_u64 v[180:181], v[246:247], 0, s[42:43]
	global_load_dwordx4 v[110:113], v[180:181], off nt
	global_load_dwordx4 v[106:109], v[180:181], off offset:16 nt
	global_load_dwordx4 v[102:105], v[180:181], off offset:128 nt
	global_load_dwordx4 v[98:101], v[180:181], off offset:144 nt
	s_waitcnt vmcnt(19)
	v_pk_fma_f32 v[94:95], v[94:95], v[142:143], v[230:231]
	v_pk_fma_f32 v[96:97], v[96:97], v[144:145], v[232:233]
	v_pk_fma_f32 v[90:91], v[90:91], v[138:139], v[234:235]
	v_pk_fma_f32 v[92:93], v[92:93], v[140:141], v[236:237]
	v_pk_fma_f32 v[86:87], v[86:87], v[134:135], v[238:239]
	v_pk_fma_f32 v[88:89], v[88:89], v[136:137], v[240:241]
	v_pk_fma_f32 v[82:83], v[82:83], v[130:131], v[242:243]
	v_pk_fma_f32 v[84:85], v[84:85], v[132:133], v[244:245]
	s_mov_b64 s[42:43], 0x40000
	v_lshl_add_u64 v[230:231], v[248:249], 0, s[42:43]
	global_store_dwordx4 v[230:231], v[94:97], off nt
	global_store_dwordx4 v[230:231], v[90:93], off offset:16 nt
	global_store_dwordx4 v[230:231], v[86:89], off offset:128 nt
	global_store_dwordx4 v[230:231], v[82:85], off offset:144 nt
	v_mul_f32_e32 v242, v94, v94
	v_fmac_f32_e32 v242, v95, v95
	v_fmac_f32_e32 v242, v96, v96
	v_fmac_f32_e32 v242, v97, v97
	v_fmac_f32_e32 v242, v90, v90
	v_fmac_f32_e32 v242, v91, v91
	v_fmac_f32_e32 v242, v92, v92
	v_fmac_f32_e32 v242, v93, v93
	v_mul_f32_e32 v243, v86, v86
	v_fmac_f32_e32 v243, v87, v87
	v_fmac_f32_e32 v243, v88, v88
	v_fmac_f32_e32 v243, v89, v89
	v_fmac_f32_e32 v243, v82, v82
	v_fmac_f32_e32 v243, v83, v83
	v_fmac_f32_e32 v243, v84, v84
	v_fmac_f32_e32 v243, v85, v85
	v_add_f32_e32 v242, v242, v243
	ds_bpermute_b32 v244, v200, v242
	v_pk_mul_f32 v[94:95], v[188:189], v[94:95]
	v_pk_mul_f32 v[96:97], v[190:191], v[96:97]
	v_pk_mul_f32 v[90:91], v[184:185], v[90:91]
	v_pk_mul_f32 v[92:93], v[186:187], v[92:93]
	v_pk_mul_f32 v[86:87], v[182:183], v[86:87]
	v_pk_mul_f32 v[88:89], v[196:197], v[88:89]
	v_pk_mul_f32 v[82:83], v[192:193], v[82:83]
	v_pk_mul_f32 v[84:85], v[194:195], v[84:85]
	v_cvt_pk_bf16_f32 v234, v94, v95
	v_cvt_pk_bf16_f32 v235, v96, v97
	v_cvt_pk_bf16_f32 v236, v90, v91
	v_cvt_pk_bf16_f32 v237, v92, v93
	v_cvt_pk_bf16_f32 v238, v86, v87
	v_cvt_pk_bf16_f32 v239, v88, v89
	v_cvt_pk_bf16_f32 v240, v82, v83
	v_cvt_pk_bf16_f32 v241, v84, v85
	s_mov_b64 s[42:43], 0x20000
	v_lshl_add_u64 v[232:233], v[250:251], 0, s[42:43]
	global_store_dwordx4 v[232:233], v[234:237], off
	global_store_dwordx4 v[232:233], v[238:241], off offset:64
	s_waitcnt lgkmcnt(0)
	v_add_f32_e32 v242, v242, v244
	ds_bpermute_b32 v244, v201, v242
	s_waitcnt lgkmcnt(0)
	v_add_f32_e32 v242, v242, v244
	s_and_saveexec_b64 s[42:43], s[38:39]
	global_atomic_add_f32 v[198:199], v242, off offset:128
	s_mov_b64 exec, s[42:43]
	s_mov_b64 s[42:43], 0x140000
	v_lshl_add_u64 v[180:181], v[246:247], 0, s[42:43]
	global_load_dwordx4 v[230:233], v[180:181], off nt
	global_load_dwordx4 v[234:237], v[180:181], off offset:16 nt
	global_load_dwordx4 v[238:241], v[180:181], off offset:128 nt
	global_load_dwordx4 v[242:245], v[180:181], off offset:144 nt
	s_mov_b64 s[42:43], 0x160000
	v_lshl_add_u64 v[180:181], v[246:247], 0, s[42:43]
	global_load_dwordx4 v[94:97], v[180:181], off nt
	global_load_dwordx4 v[90:93], v[180:181], off offset:16 nt
	global_load_dwordx4 v[86:89], v[180:181], off offset:128 nt
	global_load_dwordx4 v[82:85], v[180:181], off offset:144 nt
	s_waitcnt vmcnt(30)
	v_pk_fma_f32 v[78:79], v[78:79], v[142:143], v[126:127]
	v_pk_fma_f32 v[80:81], v[80:81], v[144:145], v[128:129]
	v_pk_fma_f32 v[74:75], v[74:75], v[138:139], v[122:123]
	v_pk_fma_f32 v[76:77], v[76:77], v[140:141], v[124:125]
	v_pk_fma_f32 v[70:71], v[70:71], v[134:135], v[118:119]
	v_pk_fma_f32 v[72:73], v[72:73], v[136:137], v[120:121]
	v_pk_fma_f32 v[66:67], v[66:67], v[130:131], v[114:115]
	v_pk_fma_f32 v[68:69], v[68:69], v[132:133], v[116:117]
	s_mov_b64 s[42:43], 0x60000
	v_lshl_add_u64 v[126:127], v[248:249], 0, s[42:43]
	global_store_dwordx4 v[126:127], v[78:81], off nt
	global_store_dwordx4 v[126:127], v[74:77], off offset:16 nt
	global_store_dwordx4 v[126:127], v[70:73], off offset:128 nt
	global_store_dwordx4 v[126:127], v[66:69], off offset:144 nt
	v_mul_f32_e32 v114, v78, v78
	v_fmac_f32_e32 v114, v79, v79
	v_fmac_f32_e32 v114, v80, v80
	v_fmac_f32_e32 v114, v81, v81
	v_fmac_f32_e32 v114, v74, v74
	v_fmac_f32_e32 v114, v75, v75
	v_fmac_f32_e32 v114, v76, v76
	v_fmac_f32_e32 v114, v77, v77
	v_mul_f32_e32 v115, v70, v70
	v_fmac_f32_e32 v115, v71, v71
	v_fmac_f32_e32 v115, v72, v72
	v_fmac_f32_e32 v115, v73, v73
	v_fmac_f32_e32 v115, v66, v66
	v_fmac_f32_e32 v115, v67, v67
	v_fmac_f32_e32 v115, v68, v68
	v_fmac_f32_e32 v115, v69, v69
	v_add_f32_e32 v114, v114, v115
	ds_bpermute_b32 v116, v200, v114
	v_pk_mul_f32 v[78:79], v[188:189], v[78:79]
	v_pk_mul_f32 v[80:81], v[190:191], v[80:81]
	v_pk_mul_f32 v[74:75], v[184:185], v[74:75]
	v_pk_mul_f32 v[76:77], v[186:187], v[76:77]
	v_pk_mul_f32 v[70:71], v[182:183], v[70:71]
	v_pk_mul_f32 v[72:73], v[196:197], v[72:73]
	v_pk_mul_f32 v[66:67], v[192:193], v[66:67]
	v_pk_mul_f32 v[68:69], v[194:195], v[68:69]
	v_cvt_pk_bf16_f32 v122, v78, v79
	v_cvt_pk_bf16_f32 v123, v80, v81
	v_cvt_pk_bf16_f32 v124, v74, v75
	v_cvt_pk_bf16_f32 v125, v76, v77
	v_cvt_pk_bf16_f32 v118, v70, v71
	v_cvt_pk_bf16_f32 v119, v72, v73
	v_cvt_pk_bf16_f32 v120, v66, v67
	v_cvt_pk_bf16_f32 v121, v68, v69
	s_mov_b64 s[42:43], 0x30000
	v_lshl_add_u64 v[128:129], v[250:251], 0, s[42:43]
	global_store_dwordx4 v[128:129], v[122:125], off
	global_store_dwordx4 v[128:129], v[118:121], off offset:64
	s_waitcnt lgkmcnt(0)
	v_add_f32_e32 v114, v114, v116
	ds_bpermute_b32 v116, v201, v114
	s_waitcnt lgkmcnt(0)
	v_add_f32_e32 v114, v114, v116
	s_and_saveexec_b64 s[42:43], s[38:39]
	global_atomic_add_f32 v[198:199], v114, off offset:192
	s_mov_b64 exec, s[42:43]
	s_waitcnt vmcnt(26)
	v_pk_fma_f32 v[62:63], v[62:63], v[142:143], v[146:147]
	v_pk_fma_f32 v[64:65], v[64:65], v[144:145], v[148:149]
	v_pk_fma_f32 v[58:59], v[58:59], v[138:139], v[150:151]
	v_pk_fma_f32 v[60:61], v[60:61], v[140:141], v[152:153]
	v_pk_fma_f32 v[54:55], v[54:55], v[134:135], v[176:177]
	v_pk_fma_f32 v[56:57], v[56:57], v[136:137], v[178:179]
	v_pk_fma_f32 v[50:51], v[50:51], v[130:131], v[202:203]
	v_pk_fma_f32 v[52:53], v[52:53], v[132:133], v[204:205]
	s_mov_b64 s[42:43], 0x100000
	v_lshl_add_u64 v[146:147], v[248:249], 0, s[42:43]
	global_store_dwordx4 v[146:147], v[62:65], off nt
	global_store_dwordx4 v[146:147], v[58:61], off offset:16 nt
	global_store_dwordx4 v[146:147], v[54:57], off offset:128 nt
	global_store_dwordx4 v[146:147], v[50:53], off offset:144 nt
	v_mul_f32_e32 v202, v62, v62
	v_fmac_f32_e32 v202, v63, v63
	v_fmac_f32_e32 v202, v64, v64
	v_fmac_f32_e32 v202, v65, v65
	v_fmac_f32_e32 v202, v58, v58
	v_fmac_f32_e32 v202, v59, v59
	v_fmac_f32_e32 v202, v60, v60
	v_fmac_f32_e32 v202, v61, v61
	v_mul_f32_e32 v203, v54, v54
	v_fmac_f32_e32 v203, v55, v55
	v_fmac_f32_e32 v203, v56, v56
	v_fmac_f32_e32 v203, v57, v57
	v_fmac_f32_e32 v203, v50, v50
	v_fmac_f32_e32 v203, v51, v51
	v_fmac_f32_e32 v203, v52, v52
	v_fmac_f32_e32 v203, v53, v53
	v_add_f32_e32 v202, v202, v203
	ds_bpermute_b32 v204, v200, v202
	v_pk_mul_f32 v[62:63], v[188:189], v[62:63]
	v_pk_mul_f32 v[64:65], v[190:191], v[64:65]
	v_pk_mul_f32 v[58:59], v[184:185], v[58:59]
	v_pk_mul_f32 v[60:61], v[186:187], v[60:61]
	v_pk_mul_f32 v[54:55], v[182:183], v[54:55]
	v_pk_mul_f32 v[56:57], v[196:197], v[56:57]
	v_pk_mul_f32 v[50:51], v[192:193], v[50:51]
	v_pk_mul_f32 v[52:53], v[194:195], v[52:53]
	v_cvt_pk_bf16_f32 v150, v62, v63
	v_cvt_pk_bf16_f32 v151, v64, v65
	v_cvt_pk_bf16_f32 v152, v58, v59
	v_cvt_pk_bf16_f32 v153, v60, v61
	v_cvt_pk_bf16_f32 v176, v54, v55
	v_cvt_pk_bf16_f32 v177, v56, v57
	v_cvt_pk_bf16_f32 v178, v50, v51
	v_cvt_pk_bf16_f32 v179, v52, v53
	s_mov_b64 s[42:43], 0x80000
	v_lshl_add_u64 v[148:149], v[250:251], 0, s[42:43]
	global_store_dwordx4 v[148:149], v[150:153], off
	global_store_dwordx4 v[148:149], v[176:179], off offset:64
	s_waitcnt lgkmcnt(0)
	v_add_f32_e32 v202, v202, v204
	ds_bpermute_b32 v204, v201, v202
	s_waitcnt lgkmcnt(0)
	v_add_f32_e32 v202, v202, v204
	s_and_saveexec_b64 s[42:43], s[38:39]
	global_atomic_add_f32 v[198:199], v202, off offset:512
	s_mov_b64 exec, s[42:43]
	s_waitcnt vmcnt(29)
	v_pk_fma_f32 v[46:47], v[46:47], v[142:143], v[110:111]
	v_pk_fma_f32 v[48:49], v[48:49], v[144:145], v[112:113]
	v_pk_fma_f32 v[42:43], v[42:43], v[138:139], v[106:107]
	v_pk_fma_f32 v[44:45], v[44:45], v[140:141], v[108:109]
	v_pk_fma_f32 v[38:39], v[38:39], v[134:135], v[102:103]
	v_pk_fma_f32 v[40:41], v[40:41], v[136:137], v[104:105]
	v_pk_fma_f32 v[34:35], v[34:35], v[130:131], v[98:99]
	v_pk_fma_f32 v[36:37], v[36:37], v[132:133], v[100:101]
	s_mov_b64 s[42:43], 0x120000
	v_lshl_add_u64 v[110:111], v[248:249], 0, s[42:43]
	global_store_dwordx4 v[110:111], v[46:49], off nt
	global_store_dwordx4 v[110:111], v[42:45], off offset:16 nt
	global_store_dwordx4 v[110:111], v[38:41], off offset:128 nt
	global_store_dwordx4 v[110:111], v[34:37], off offset:144 nt
	v_mul_f32_e32 v98, v46, v46
	v_fmac_f32_e32 v98, v47, v47
	v_fmac_f32_e32 v98, v48, v48
	v_fmac_f32_e32 v98, v49, v49
	v_fmac_f32_e32 v98, v42, v42
	v_fmac_f32_e32 v98, v43, v43
	v_fmac_f32_e32 v98, v44, v44
	v_fmac_f32_e32 v98, v45, v45
	v_mul_f32_e32 v99, v38, v38
	v_fmac_f32_e32 v99, v39, v39
	v_fmac_f32_e32 v99, v40, v40
	v_fmac_f32_e32 v99, v41, v41
	v_fmac_f32_e32 v99, v34, v34
	v_fmac_f32_e32 v99, v35, v35
	v_fmac_f32_e32 v99, v36, v36
	v_fmac_f32_e32 v99, v37, v37
	v_add_f32_e32 v98, v98, v99
	ds_bpermute_b32 v100, v200, v98
	v_pk_mul_f32 v[46:47], v[188:189], v[46:47]
	v_pk_mul_f32 v[48:49], v[190:191], v[48:49]
	v_pk_mul_f32 v[42:43], v[184:185], v[42:43]
	v_pk_mul_f32 v[44:45], v[186:187], v[44:45]
	v_pk_mul_f32 v[38:39], v[182:183], v[38:39]
	v_pk_mul_f32 v[40:41], v[196:197], v[40:41]
	v_pk_mul_f32 v[34:35], v[192:193], v[34:35]
	v_pk_mul_f32 v[36:37], v[194:195], v[36:37]
	v_cvt_pk_bf16_f32 v106, v46, v47
	v_cvt_pk_bf16_f32 v107, v48, v49
	v_cvt_pk_bf16_f32 v108, v42, v43
	v_cvt_pk_bf16_f32 v109, v44, v45
	v_cvt_pk_bf16_f32 v102, v38, v39
	v_cvt_pk_bf16_f32 v103, v40, v41
	v_cvt_pk_bf16_f32 v104, v34, v35
	v_cvt_pk_bf16_f32 v105, v36, v37
	s_mov_b64 s[42:43], 0x90000
	v_lshl_add_u64 v[112:113], v[250:251], 0, s[42:43]
	global_store_dwordx4 v[112:113], v[106:109], off
	global_store_dwordx4 v[112:113], v[102:105], off offset:64
	s_waitcnt lgkmcnt(0)
	v_add_f32_e32 v98, v98, v100
	ds_bpermute_b32 v100, v201, v98
	s_waitcnt lgkmcnt(0)
	v_add_f32_e32 v98, v98, v100
	s_and_saveexec_b64 s[42:43], s[38:39]
	global_atomic_add_f32 v[198:199], v98, off offset:576
	s_mov_b64 exec, s[42:43]
	s_waitcnt vmcnt(25)
	v_pk_fma_f32 v[30:31], v[30:31], v[142:143], v[230:231]
	v_pk_fma_f32 v[32:33], v[32:33], v[144:145], v[232:233]
	v_pk_fma_f32 v[26:27], v[26:27], v[138:139], v[234:235]
	v_pk_fma_f32 v[28:29], v[28:29], v[140:141], v[236:237]
	v_pk_fma_f32 v[22:23], v[22:23], v[134:135], v[238:239]
	v_pk_fma_f32 v[24:25], v[24:25], v[136:137], v[240:241]
	v_pk_fma_f32 v[18:19], v[18:19], v[130:131], v[242:243]
	v_pk_fma_f32 v[20:21], v[20:21], v[132:133], v[244:245]
	s_mov_b64 s[42:43], 0x140000
	v_lshl_add_u64 v[230:231], v[248:249], 0, s[42:43]
	global_store_dwordx4 v[230:231], v[30:33], off nt
	global_store_dwordx4 v[230:231], v[26:29], off offset:16 nt
	global_store_dwordx4 v[230:231], v[22:25], off offset:128 nt
	global_store_dwordx4 v[230:231], v[18:21], off offset:144 nt
	v_mul_f32_e32 v242, v30, v30
	v_fmac_f32_e32 v242, v31, v31
	v_fmac_f32_e32 v242, v32, v32
	v_fmac_f32_e32 v242, v33, v33
	v_fmac_f32_e32 v242, v26, v26
	v_fmac_f32_e32 v242, v27, v27
	v_fmac_f32_e32 v242, v28, v28
	v_fmac_f32_e32 v242, v29, v29
	v_mul_f32_e32 v243, v22, v22
	v_fmac_f32_e32 v243, v23, v23
	v_fmac_f32_e32 v243, v24, v24
	v_fmac_f32_e32 v243, v25, v25
	v_fmac_f32_e32 v243, v18, v18
	v_fmac_f32_e32 v243, v19, v19
	v_fmac_f32_e32 v243, v20, v20
	v_fmac_f32_e32 v243, v21, v21
	v_add_f32_e32 v242, v242, v243
	ds_bpermute_b32 v244, v200, v242
	v_pk_mul_f32 v[30:31], v[188:189], v[30:31]
	v_pk_mul_f32 v[32:33], v[190:191], v[32:33]
	v_pk_mul_f32 v[26:27], v[184:185], v[26:27]
	v_pk_mul_f32 v[28:29], v[186:187], v[28:29]
	v_pk_mul_f32 v[22:23], v[182:183], v[22:23]
	v_pk_mul_f32 v[24:25], v[196:197], v[24:25]
	v_pk_mul_f32 v[18:19], v[192:193], v[18:19]
	v_pk_mul_f32 v[20:21], v[194:195], v[20:21]
	v_cvt_pk_bf16_f32 v234, v30, v31
	v_cvt_pk_bf16_f32 v235, v32, v33
	v_cvt_pk_bf16_f32 v236, v26, v27
	v_cvt_pk_bf16_f32 v237, v28, v29
	v_cvt_pk_bf16_f32 v238, v22, v23
	v_cvt_pk_bf16_f32 v239, v24, v25
	v_cvt_pk_bf16_f32 v240, v18, v19
	v_cvt_pk_bf16_f32 v241, v20, v21
	s_mov_b64 s[42:43], 0xa0000
	v_lshl_add_u64 v[232:233], v[250:251], 0, s[42:43]
	global_store_dwordx4 v[232:233], v[234:237], off
	global_store_dwordx4 v[232:233], v[238:241], off offset:64
	s_waitcnt lgkmcnt(0)
	v_add_f32_e32 v242, v242, v244
	ds_bpermute_b32 v244, v201, v242
	s_waitcnt lgkmcnt(0)
	v_add_f32_e32 v242, v242, v244
	s_and_saveexec_b64 s[42:43], s[38:39]
	global_atomic_add_f32 v[198:199], v242, off offset:640
	s_mov_b64 exec, s[42:43]
	s_waitcnt vmcnt(28)
	v_pk_fma_f32 v[14:15], v[14:15], v[142:143], v[94:95]
	v_pk_fma_f32 v[16:17], v[16:17], v[144:145], v[96:97]
	v_pk_fma_f32 v[10:11], v[10:11], v[138:139], v[90:91]
	v_pk_fma_f32 v[12:13], v[12:13], v[140:141], v[92:93]
	v_pk_fma_f32 v[6:7], v[6:7], v[134:135], v[86:87]
	v_pk_fma_f32 v[8:9], v[8:9], v[136:137], v[88:89]
	v_pk_fma_f32 v[2:3], v[2:3], v[130:131], v[82:83]
	v_pk_fma_f32 v[4:5], v[4:5], v[132:133], v[84:85]
	s_mov_b64 s[42:43], 0x160000
	v_lshl_add_u64 v[94:95], v[248:249], 0, s[42:43]
	global_store_dwordx4 v[94:95], v[14:17], off nt
	global_store_dwordx4 v[94:95], v[10:13], off offset:16 nt
	global_store_dwordx4 v[94:95], v[6:9], off offset:128 nt
	global_store_dwordx4 v[94:95], v[2:5], off offset:144 nt
	v_mul_f32_e32 v82, v14, v14
	v_fmac_f32_e32 v82, v15, v15
	v_fmac_f32_e32 v82, v16, v16
	v_fmac_f32_e32 v82, v17, v17
	v_fmac_f32_e32 v82, v10, v10
	v_fmac_f32_e32 v82, v11, v11
	v_fmac_f32_e32 v82, v12, v12
	v_fmac_f32_e32 v82, v13, v13
	v_mul_f32_e32 v83, v6, v6
	v_fmac_f32_e32 v83, v7, v7
	v_fmac_f32_e32 v83, v8, v8
	v_fmac_f32_e32 v83, v9, v9
	v_fmac_f32_e32 v83, v2, v2
	v_fmac_f32_e32 v83, v3, v3
	v_fmac_f32_e32 v83, v4, v4
	v_fmac_f32_e32 v83, v5, v5
	v_add_f32_e32 v82, v82, v83
	ds_bpermute_b32 v84, v200, v82
	v_pk_mul_f32 v[14:15], v[188:189], v[14:15]
	v_pk_mul_f32 v[16:17], v[190:191], v[16:17]
	v_pk_mul_f32 v[10:11], v[184:185], v[10:11]
	v_pk_mul_f32 v[12:13], v[186:187], v[12:13]
	v_pk_mul_f32 v[6:7], v[182:183], v[6:7]
	v_pk_mul_f32 v[8:9], v[196:197], v[8:9]
	v_pk_mul_f32 v[2:3], v[192:193], v[2:3]
	v_pk_mul_f32 v[4:5], v[194:195], v[4:5]
	v_cvt_pk_bf16_f32 v90, v14, v15
	v_cvt_pk_bf16_f32 v91, v16, v17
	v_cvt_pk_bf16_f32 v92, v10, v11
	v_cvt_pk_bf16_f32 v93, v12, v13
	v_cvt_pk_bf16_f32 v86, v6, v7
	v_cvt_pk_bf16_f32 v87, v8, v9
	v_cvt_pk_bf16_f32 v88, v2, v3
	v_cvt_pk_bf16_f32 v89, v4, v5
	s_mov_b64 s[42:43], 0xb0000
	v_lshl_add_u64 v[96:97], v[250:251], 0, s[42:43]
	global_store_dwordx4 v[96:97], v[90:93], off
	global_store_dwordx4 v[96:97], v[86:89], off offset:64
	s_waitcnt lgkmcnt(0)
	v_add_f32_e32 v82, v82, v84
	ds_bpermute_b32 v84, v201, v82
	s_waitcnt lgkmcnt(0)
	v_add_f32_e32 v82, v82, v84
	s_and_saveexec_b64 s[42:43], s[38:39]
	global_atomic_add_f32 v[198:199], v82, off offset:704
	s_mov_b64 exec, s[42:43]
	s_branch .LBB0_487
.Lres_noaout:
	global_load_dwordx4 v[230:233], v[246:247], off nt
	global_load_dwordx4 v[234:237], v[246:247], off offset:16 nt
	global_load_dwordx4 v[238:241], v[246:247], off offset:128 nt
	global_load_dwordx4 v[242:245], v[246:247], off offset:144 nt
	s_mov_b64 s[42:43], 0x20000
	v_lshl_add_u64 v[180:181], v[246:247], 0, s[42:43]
	global_load_dwordx4 v[146:149], v[180:181], off nt
	global_load_dwordx4 v[150:153], v[180:181], off offset:16 nt
	global_load_dwordx4 v[176:179], v[180:181], off offset:128 nt
	global_load_dwordx4 v[202:205], v[180:181], off offset:144 nt
	s_waitcnt vmcnt(4)
	v_pk_fma_f32 v[126:127], v[126:127], v[142:143], v[230:231]
	v_pk_fma_f32 v[128:129], v[128:129], v[144:145], v[232:233]
	v_pk_fma_f32 v[122:123], v[122:123], v[138:139], v[234:235]
	v_pk_fma_f32 v[124:125], v[124:125], v[140:141], v[236:237]
	v_pk_fma_f32 v[118:119], v[118:119], v[134:135], v[238:239]
	v_pk_fma_f32 v[120:121], v[120:121], v[136:137], v[240:241]
	v_pk_fma_f32 v[114:115], v[114:115], v[130:131], v[242:243]
	v_pk_fma_f32 v[116:117], v[116:117], v[132:133], v[244:245]
	global_store_dwordx4 v[248:249], v[126:129], off nt
	global_store_dwordx4 v[248:249], v[122:125], off offset:16 nt
	global_store_dwordx4 v[248:249], v[118:121], off offset:128 nt
	global_store_dwordx4 v[248:249], v[114:117], off offset:144 nt
	s_mov_b64 s[42:43], 0x40000
	v_lshl_add_u64 v[180:181], v[246:247], 0, s[42:43]
	global_load_dwordx4 v[230:233], v[180:181], off nt
	global_load_dwordx4 v[234:237], v[180:181], off offset:16 nt
	global_load_dwordx4 v[238:241], v[180:181], off offset:128 nt
	global_load_dwordx4 v[242:245], v[180:181], off offset:144 nt
	s_mov_b64 s[42:43], 0x60000
	v_lshl_add_u64 v[180:181], v[246:247], 0, s[42:43]
	global_load_dwordx4 v[126:129], v[180:181], off nt
	global_load_dwordx4 v[122:125], v[180:181], off offset:16 nt
	global_load_dwordx4 v[118:121], v[180:181], off offset:128 nt
	global_load_dwordx4 v[114:117], v[180:181], off offset:144 nt
	s_waitcnt vmcnt(12)
	v_pk_fma_f32 v[110:111], v[110:111], v[142:143], v[146:147]
	v_pk_fma_f32 v[112:113], v[112:113], v[144:145], v[148:149]
	v_pk_fma_f32 v[106:107], v[106:107], v[138:139], v[150:151]
	v_pk_fma_f32 v[108:109], v[108:109], v[140:141], v[152:153]
	v_pk_fma_f32 v[102:103], v[102:103], v[134:135], v[176:177]
	v_pk_fma_f32 v[104:105], v[104:105], v[136:137], v[178:179]
	v_pk_fma_f32 v[98:99], v[98:99], v[130:131], v[202:203]
	v_pk_fma_f32 v[100:101], v[100:101], v[132:133], v[204:205]
	s_mov_b64 s[42:43], 0x20000
	v_lshl_add_u64 v[146:147], v[248:249], 0, s[42:43]
	global_store_dwordx4 v[146:147], v[110:113], off nt
	global_store_dwordx4 v[146:147], v[106:109], off offset:16 nt
	global_store_dwordx4 v[146:147], v[102:105], off offset:128 nt
	global_store_dwordx4 v[146:147], v[98:101], off offset:144 nt
	s_mov_b64 s[42:43], 0x100000
	v_lshl_add_u64 v[180:181], v[246:247], 0, s[42:43]
	global_load_dwordx4 v[146:149], v[180:181], off nt
	global_load_dwordx4 v[150:153], v[180:181], off offset:16 nt
	global_load_dwordx4 v[176:179], v[180:181], off offset:128 nt
	global_load_dwordx4 v[202:205], v[180:181], off offset:144 nt
	s_mov_b64 s[42:43], 0x120000
	v_lshl_add_u64 v[180:181], v[246:247], 0, s[42:43]
	global_load_dwordx4 v[110:113], v[180:181], off nt
	global_load_dwordx4 v[106:109], v[180:181], off offset:16 nt
	global_load_dwordx4 v[102:105], v[180:181], off offset:128 nt
	global_load_dwordx4 v[98:101], v[180:181], off offset:144 nt
	s_waitcnt vmcnt(16)
	v_pk_fma_f32 v[94:95], v[94:95], v[142:143], v[230:231]
	v_pk_fma_f32 v[96:97], v[96:97], v[144:145], v[232:233]
	v_pk_fma_f32 v[90:91], v[90:91], v[138:139], v[234:235]
	v_pk_fma_f32 v[92:93], v[92:93], v[140:141], v[236:237]
	v_pk_fma_f32 v[86:87], v[86:87], v[134:135], v[238:239]
	v_pk_fma_f32 v[88:89], v[88:89], v[136:137], v[240:241]
	v_pk_fma_f32 v[82:83], v[82:83], v[130:131], v[242:243]
	v_pk_fma_f32 v[84:85], v[84:85], v[132:133], v[244:245]
	s_mov_b64 s[42:43], 0x40000
	v_lshl_add_u64 v[230:231], v[248:249], 0, s[42:43]
	global_store_dwordx4 v[230:231], v[94:97], off nt
	global_store_dwordx4 v[230:231], v[90:93], off offset:16 nt
	global_store_dwordx4 v[230:231], v[86:89], off offset:128 nt
	global_store_dwordx4 v[230:231], v[82:85], off offset:144 nt
	s_mov_b64 s[42:43], 0x140000
	v_lshl_add_u64 v[180:181], v[246:247], 0, s[42:43]
	global_load_dwordx4 v[230:233], v[180:181], off nt
	global_load_dwordx4 v[234:237], v[180:181], off offset:16 nt
	global_load_dwordx4 v[238:241], v[180:181], off offset:128 nt
	global_load_dwordx4 v[242:245], v[180:181], off offset:144 nt
	s_mov_b64 s[42:43], 0x160000
	v_lshl_add_u64 v[180:181], v[246:247], 0, s[42:43]
	global_load_dwordx4 v[94:97], v[180:181], off nt
	global_load_dwordx4 v[90:93], v[180:181], off offset:16 nt
	global_load_dwordx4 v[86:89], v[180:181], off offset:128 nt
	global_load_dwordx4 v[82:85], v[180:181], off offset:144 nt
	s_waitcnt vmcnt(24)
	v_pk_fma_f32 v[78:79], v[78:79], v[142:143], v[126:127]
	v_pk_fma_f32 v[80:81], v[80:81], v[144:145], v[128:129]
	v_pk_fma_f32 v[74:75], v[74:75], v[138:139], v[122:123]
	v_pk_fma_f32 v[76:77], v[76:77], v[140:141], v[124:125]
	v_pk_fma_f32 v[70:71], v[70:71], v[134:135], v[118:119]
	v_pk_fma_f32 v[72:73], v[72:73], v[136:137], v[120:121]
	v_pk_fma_f32 v[66:67], v[66:67], v[130:131], v[114:115]
	v_pk_fma_f32 v[68:69], v[68:69], v[132:133], v[116:117]
	s_mov_b64 s[42:43], 0x60000
	v_lshl_add_u64 v[126:127], v[248:249], 0, s[42:43]
	global_store_dwordx4 v[126:127], v[78:81], off nt
	global_store_dwordx4 v[126:127], v[74:77], off offset:16 nt
	global_store_dwordx4 v[126:127], v[70:73], off offset:128 nt
	global_store_dwordx4 v[126:127], v[66:69], off offset:144 nt
	s_waitcnt vmcnt(20)
	v_pk_fma_f32 v[62:63], v[62:63], v[142:143], v[146:147]
	v_pk_fma_f32 v[64:65], v[64:65], v[144:145], v[148:149]
	v_pk_fma_f32 v[58:59], v[58:59], v[138:139], v[150:151]
	v_pk_fma_f32 v[60:61], v[60:61], v[140:141], v[152:153]
	v_pk_fma_f32 v[54:55], v[54:55], v[134:135], v[176:177]
	v_pk_fma_f32 v[56:57], v[56:57], v[136:137], v[178:179]
	v_pk_fma_f32 v[50:51], v[50:51], v[130:131], v[202:203]
	v_pk_fma_f32 v[52:53], v[52:53], v[132:133], v[204:205]
	s_mov_b64 s[42:43], 0x100000
	v_lshl_add_u64 v[146:147], v[248:249], 0, s[42:43]
	global_store_dwordx4 v[146:147], v[62:65], off nt
	global_store_dwordx4 v[146:147], v[58:61], off offset:16 nt
	global_store_dwordx4 v[146:147], v[54:57], off offset:128 nt
	global_store_dwordx4 v[146:147], v[50:53], off offset:144 nt
	s_waitcnt vmcnt(20)
	v_pk_fma_f32 v[46:47], v[46:47], v[142:143], v[110:111]
	v_pk_fma_f32 v[48:49], v[48:49], v[144:145], v[112:113]
	v_pk_fma_f32 v[42:43], v[42:43], v[138:139], v[106:107]
	v_pk_fma_f32 v[44:45], v[44:45], v[140:141], v[108:109]
	v_pk_fma_f32 v[38:39], v[38:39], v[134:135], v[102:103]
	v_pk_fma_f32 v[40:41], v[40:41], v[136:137], v[104:105]
	v_pk_fma_f32 v[34:35], v[34:35], v[130:131], v[98:99]
	v_pk_fma_f32 v[36:37], v[36:37], v[132:133], v[100:101]
	s_mov_b64 s[42:43], 0x120000
	v_lshl_add_u64 v[110:111], v[248:249], 0, s[42:43]
	global_store_dwordx4 v[110:111], v[46:49], off nt
	global_store_dwordx4 v[110:111], v[42:45], off offset:16 nt
	global_store_dwordx4 v[110:111], v[38:41], off offset:128 nt
	global_store_dwordx4 v[110:111], v[34:37], off offset:144 nt
	s_waitcnt vmcnt(16)
	v_pk_fma_f32 v[30:31], v[30:31], v[142:143], v[230:231]
	v_pk_fma_f32 v[32:33], v[32:33], v[144:145], v[232:233]
	v_pk_fma_f32 v[26:27], v[26:27], v[138:139], v[234:235]
	v_pk_fma_f32 v[28:29], v[28:29], v[140:141], v[236:237]
	v_pk_fma_f32 v[22:23], v[22:23], v[134:135], v[238:239]
	v_pk_fma_f32 v[24:25], v[24:25], v[136:137], v[240:241]
	v_pk_fma_f32 v[18:19], v[18:19], v[130:131], v[242:243]
	v_pk_fma_f32 v[20:21], v[20:21], v[132:133], v[244:245]
	s_mov_b64 s[42:43], 0x140000
	v_lshl_add_u64 v[230:231], v[248:249], 0, s[42:43]
	global_store_dwordx4 v[230:231], v[30:33], off nt
	global_store_dwordx4 v[230:231], v[26:29], off offset:16 nt
	global_store_dwordx4 v[230:231], v[22:25], off offset:128 nt
	global_store_dwordx4 v[230:231], v[18:21], off offset:144 nt
	s_waitcnt vmcnt(16)
	v_pk_fma_f32 v[14:15], v[14:15], v[142:143], v[94:95]
	v_pk_fma_f32 v[16:17], v[16:17], v[144:145], v[96:97]
	v_pk_fma_f32 v[10:11], v[10:11], v[138:139], v[90:91]
	v_pk_fma_f32 v[12:13], v[12:13], v[140:141], v[92:93]
	v_pk_fma_f32 v[6:7], v[6:7], v[134:135], v[86:87]
	v_pk_fma_f32 v[8:9], v[8:9], v[136:137], v[88:89]
	v_pk_fma_f32 v[2:3], v[2:3], v[130:131], v[82:83]
	v_pk_fma_f32 v[4:5], v[4:5], v[132:133], v[84:85]
	s_mov_b64 s[42:43], 0x160000
	v_lshl_add_u64 v[94:95], v[248:249], 0, s[42:43]
	global_store_dwordx4 v[94:95], v[14:17], off nt
	global_store_dwordx4 v[94:95], v[10:13], off offset:16 nt
	global_store_dwordx4 v[94:95], v[6:9], off offset:128 nt
	global_store_dwordx4 v[94:95], v[2:5], off offset:144 nt
	s_branch .LBB0_487
